# combo12 + K-loop headers aligned to 256 bytes
# baseline (speedup 1.0000x reference)
; template <class Epi, class Sched, bool ALIGN_EPI = false, bool SP2 = false, bool ACHUNK = false>
; __device__ __forceinline__ void gemm_phase(PG8_LAS unsigned char* lds, const Gemm g, const Sched& S, const Epi& E) {
;     ...
;         const bool has_next = S.next(ui + 1, nxt);
;         const char* nA = has_next ? (const char*)g.A + (size_t)nxt.pm * tstepA : cA; const char* nB = has_next ? (const char*)g.Bt + (size_t)nxt.pn * tstepB : cB;
;         for (int t = 0; t < nt; t += 2) {
;             const bool last = (t == nt - 2);
;             if constexpr (Epi::HAS_MID) { if (t == Epi::MID_T) E.mid(acc, cur, wr, wc, fr, fq, ShflDev{}); }
;             const char* a1 = cA + (size_t)(t + 1) * kstep;
;             const char* a2 = last ? nA : cA + (size_t)(t + 2) * kstep; const char* b2 = last ? nB : cB + (size_t)(t + 2) * kstep;
;             const char* a3 = a2 + kstep; const char* b3 = b2 + kstep;
.LBB0_51:
	s_add_u32 s20, s20, 0x80
	s_addc_u32 s21, s21, 0
	s_add_u32 s44, s18, 0x100
	s_addc_u32 s45, s19, 0
	s_mov_b32 s18, 0
	.p2align	8

; #define PG8_STAGE(bufoff, gbase, voff) do { _Pragma("unroll") for (int _i = 0; _i < 2; ++_i) \
;         __builtin_amdgcn_global_load_lds((const unsigned*)((const char*)(gbase) + (voff)[_i]), (PG8_LAS unsigned*)(lds + (bufoff) + ldsw + _i * 8192), 16, 0, 0); } while (0)
; #define PG8_LDA(dst, b, h) do { _Pragma("unroll") for (int m = 0; m < 4; ++m) _Pragma("unroll") for (int k = 0; k < 2; ++k) dst[m][k] = *(const PG8_LAS bf16x8*)(lds + PG8_SA(b, h) + aoff + m * 2048 + k * 1024); } while (0)
; #define PG8_LDB(dst, b, h) do { _Pragma("unroll") for (int n = 0; n < 2; ++n) _Pragma("unroll") for (int k = 0; k < 2; ++k) dst[n][k] = *(const PG8_LAS bf16x8*)(lds + PG8_SB(b, h) + boff + n * 2048 + k * 1024); } while (0)
; #define PG8_MMA(ai, bj, At, Bt) do { __builtin_amdgcn_s_setprio(1); _Pragma("unroll") for (int m = 0; m < 4; ++m) _Pragma("unroll") for (int n = 0; n < 2; ++n) _Pragma("unroll") for (int k = 0; k < 2; ++k) \
;         acc[ai][bj][m][n] = __builtin_amdgcn_mfma_f32_16x16x32_bf16(Bt[n][k], At[m][k], acc[ai][bj][m][n], 0, 0, 0); __builtin_amdgcn_s_setprio(0); } while (0)
; #define PG8_WAIT_V(n) asm volatile("s_waitcnt vmcnt(" #n ")" ::: "memory")
; #define PG8_WAIT_L(n) asm volatile("s_waitcnt lgkmcnt(" #n ")" ::: "memory")
; #define PG8_BAR __builtin_amdgcn_s_barrier()
; template <class Epi, class Sched, bool ALIGN_EPI = false, bool SP2 = false, bool ACHUNK = false>
; __device__ __forceinline__ void gemm_phase(PG8_LAS unsigned char* lds, const Gemm g, const Sched& S, const Epi& E) {
;     ...
;             const char* a1 = cA + (size_t)(t + 1) * kstep;
;             const char* a2 = last ? nA : cA + (size_t)(t + 2) * kstep; const char* b2 = last ? nB : cB + (size_t)(t + 2) * kstep;
;             const char* a3 = a2 + kstep; const char* b3 = b2 + kstep;
;             if (last && has_next) S.a_ready(nxt);
;             if constexpr (SP2) {
;             PG8_LDB(B0, 0, 0); PG8_LDB(B1, 0, 1); PG8_SCHED; PG8_LDA(At, 0, 0); PG8_STAGE(PG8_SA(1, 1), a1 + hstepA, voffA);
;             PG8_WAIT_V(8); PG8_WAIT_L(0); PG8_BAR; PG8_MMA(0, 0, At, B0); PG8_MMA(0, 1, At, B1); PG8_BAR; PG8_SCHED;
;             PG8_LDA(At, 0, 1); PG8_STAGE(PG8_SB(0, 0), b2, voffB); PG8_STAGE(PG8_SB(0, 1), b2 + hstepB, voffB); PG8_STAGE(PG8_SA(0, 0), a2, voffA);
;             PG8_WAIT_V(8); PG8_WAIT_L(0); PG8_BAR; PG8_MMA(1, 0, At, B0); PG8_MMA(1, 1, At, B1); PG8_BAR; PG8_SCHED;
.LBB0_106:
	s_andn2_b64 vcc, exec, s[44:45]
	s_nop 0
	s_cbranch_vccnz .LBB0_110
	s_add_u32 s8, s4, 0x100
	s_addc_u32 s9, s5, 0
	s_add_u32 s0, s6, 0x80
	s_addc_u32 s1, s7, 0
	s_mov_b32 s4, 0
	s_add_i32 s6, s4, 2
	s_add_u32 s7, s0, 0x80
	s_addc_u32 s5, s1, 0
	s_add_i32 s77, 0, 0x10000
	s_cmp_eq_u32 s54, s4
	s_cselect_b32 s5, s49, s5
	s_cselect_b32 s4, s48, s7
	v_add_u32_e32 v2, s77, v224
	s_cselect_b32 s79, s51, s9
	s_cselect_b32 s78, s50, s8
	s_add_i32 s7, 0, 0x14000
	s_waitcnt lgkmcnt(0)
	ds_read_b128 v[36:39], v2
	ds_read_b128 v[40:43], v2 offset:1024
	ds_read_b128 v[44:47], v2 offset:2048
	ds_read_b128 v[48:51], v2 offset:3072
	v_add_u32_e32 v2, s7, v224
	ds_read_b128 v[52:55], v2
	ds_read_b128 v[56:59], v2 offset:1024
	ds_read_b128 v[60:63], v2 offset:2048
	ds_read_b128 v[64:67], v2 offset:3072
	s_add_u32 s98, s0, s28
	s_addc_u32 s99, s1, s29
	s_add_i32 m0, s25, 0xc000
	ds_read_b128 v[164:167], v238
	ds_read_b128 v[168:171], v238 offset:1024
	ds_read_b128 v[184:187], v238 offset:2048
	ds_read_b128 v[188:191], v238 offset:3072
	ds_read_b128 v[198:201], v238 offset:4096
	ds_read_b128 v[202:205], v238 offset:5120
	ds_read_b128 v[206:209], v238 offset:6144
	ds_read_b128 v[210:213], v238 offset:7168
	global_load_lds_dwordx4 v172, s[98:99]
	s_add_i32 m0, s25, 0xe000
	s_nop 0
	global_load_lds_dwordx4 v176, s[98:99]
	s_waitcnt vmcnt(8)
	s_waitcnt lgkmcnt(0)
	s_barrier
	s_setprio 1
	v_mfma_f32_16x16x32_bf16 v[148:151], v[36:39], v[164:167], 0
	v_mfma_f32_16x16x32_bf16 v[152:155], v[44:47], v[164:167], 0
	v_mfma_f32_16x16x32_bf16 v[132:135], v[36:39], v[184:187], 0
	v_mfma_f32_16x16x32_bf16 v[140:143], v[44:47], v[184:187], 0
	v_mfma_f32_16x16x32_bf16 v[136:139], v[36:39], v[198:201], 0
	v_mfma_f32_16x16x32_bf16 v[144:147], v[44:47], v[198:201], 0
	v_mfma_f32_16x16x32_bf16 v[160:163], v[36:39], v[206:209], 0
	v_mfma_f32_16x16x32_bf16 v[156:159], v[44:47], v[206:209], 0
	v_mfma_f32_16x16x32_bf16 v[148:151], v[40:43], v[168:171], v[148:151]
	v_mfma_f32_16x16x32_bf16 v[152:155], v[48:51], v[168:171], v[152:155]
	v_mfma_f32_16x16x32_bf16 v[132:135], v[40:43], v[188:191], v[132:135]
	v_mfma_f32_16x16x32_bf16 v[140:143], v[48:51], v[188:191], v[140:143]
	v_mfma_f32_16x16x32_bf16 v[136:139], v[40:43], v[202:205], v[136:139]
	v_mfma_f32_16x16x32_bf16 v[144:147], v[48:51], v[202:205], v[144:147]
	v_mfma_f32_16x16x32_bf16 v[160:163], v[40:43], v[210:213], v[160:163]
	v_mfma_f32_16x16x32_bf16 v[156:159], v[48:51], v[210:213], v[156:159]
	s_setprio 0
	s_setprio 1
	v_mfma_f32_16x16x32_bf16 v[124:127], v[52:55], v[164:167], 0
	v_mfma_f32_16x16x32_bf16 v[128:131], v[60:63], v[164:167], 0
	v_mfma_f32_16x16x32_bf16 v[116:119], v[52:55], v[184:187], 0
	v_mfma_f32_16x16x32_bf16 v[120:123], v[60:63], v[184:187], 0
	v_mfma_f32_16x16x32_bf16 v[112:115], v[52:55], v[198:201], 0
	v_mfma_f32_16x16x32_bf16 v[108:111], v[60:63], v[198:201], 0
	v_mfma_f32_16x16x32_bf16 v[104:107], v[52:55], v[206:209], 0
	v_mfma_f32_16x16x32_bf16 v[100:103], v[60:63], v[206:209], 0
	v_mfma_f32_16x16x32_bf16 v[124:127], v[56:59], v[168:171], v[124:127]
	v_mfma_f32_16x16x32_bf16 v[128:131], v[64:67], v[168:171], v[128:131]
	v_mfma_f32_16x16x32_bf16 v[116:119], v[56:59], v[188:191], v[116:119]
	v_mfma_f32_16x16x32_bf16 v[120:123], v[64:67], v[188:191], v[120:123]
	v_mfma_f32_16x16x32_bf16 v[112:115], v[56:59], v[202:205], v[112:115]
	v_mfma_f32_16x16x32_bf16 v[108:111], v[64:67], v[202:205], v[108:111]
	v_mfma_f32_16x16x32_bf16 v[104:107], v[56:59], v[210:213], v[104:107]
	v_mfma_f32_16x16x32_bf16 v[100:103], v[64:67], v[210:213], v[100:103]
	s_setprio 0
	s_barrier
	s_add_i32 s77, s77, s17
	s_add_u32 s98, s78, s18
	s_addc_u32 s99, s79, s19
	s_mov_b32 m0, s77
	ds_read_b128 v[164:167], v238 offset:16384
	ds_read_b128 v[168:171], v238 offset:17408
	ds_read_b128 v[184:187], v238 offset:18432
	ds_read_b128 v[188:191], v238 offset:19456
	ds_read_b128 v[198:201], v238 offset:20480
	ds_read_b128 v[202:205], v238 offset:21504
	ds_read_b128 v[206:209], v238 offset:22528
	ds_read_b128 v[210:213], v238 offset:23552
	global_load_lds_dwordx4 v174, s[78:79]
	s_add_i32 m0, s77, 0x2000
	s_add_i32 s7, s7, s17
	global_load_lds_dwordx4 v178, s[78:79]
	s_mov_b32 m0, s7
	s_nop 0
	global_load_lds_dwordx4 v174, s[98:99]
	s_add_i32 m0, s7, 0x2000
	s_nop 0
	global_load_lds_dwordx4 v178, s[98:99]
	s_mov_b32 m0, s25
	s_nop 0
	global_load_lds_dwordx4 v172, s[4:5]
	s_mov_b32 m0, s26
	s_nop 0
	global_load_lds_dwordx4 v176, s[4:5]
	s_waitcnt vmcnt(8)
	s_waitcnt lgkmcnt(0)
	s_barrier
	s_setprio 1
	v_mfma_f32_16x16x32_bf16 v[96:99], v[36:39], v[164:167], 0
	v_mfma_f32_16x16x32_bf16 v[92:95], v[44:47], v[164:167], 0
	v_mfma_f32_16x16x32_bf16 v[88:91], v[36:39], v[184:187], 0
	v_mfma_f32_16x16x32_bf16 v[84:87], v[44:47], v[184:187], 0
	v_mfma_f32_16x16x32_bf16 v[80:83], v[36:39], v[198:201], 0
	v_mfma_f32_16x16x32_bf16 v[76:79], v[44:47], v[198:201], 0
	v_mfma_f32_16x16x32_bf16 v[36:39], v[36:39], v[206:209], 0
	v_mfma_f32_16x16x32_bf16 v[96:99], v[40:43], v[168:171], v[96:99]
	v_mfma_f32_16x16x32_bf16 v[92:95], v[48:51], v[168:171], v[92:95]
	v_mfma_f32_16x16x32_bf16 v[88:91], v[40:43], v[188:191], v[88:91]
	v_mfma_f32_16x16x32_bf16 v[84:87], v[48:51], v[188:191], v[84:87]
	v_mfma_f32_16x16x32_bf16 v[80:83], v[40:43], v[202:205], v[80:83]
	v_mfma_f32_16x16x32_bf16 v[76:79], v[48:51], v[202:205], v[76:79]
	v_mfma_f32_16x16x32_bf16 v[36:39], v[40:43], v[210:213], v[36:39]
	v_mfma_f32_16x16x32_bf16 v[40:43], v[44:47], v[206:209], 0
	v_mfma_f32_16x16x32_bf16 v[40:43], v[48:51], v[210:213], v[40:43]
	s_setprio 0
	s_setprio 1
	v_mfma_f32_16x16x32_bf16 v[28:31], v[52:55], v[164:167], 0
	v_mfma_f32_16x16x32_bf16 v[32:35], v[60:63], v[164:167], 0
	v_mfma_f32_16x16x32_bf16 v[20:23], v[52:55], v[184:187], 0
	v_mfma_f32_16x16x32_bf16 v[24:27], v[60:63], v[184:187], 0
	v_mfma_f32_16x16x32_bf16 v[16:19], v[52:55], v[198:201], 0
	v_mfma_f32_16x16x32_bf16 v[12:15], v[60:63], v[198:201], 0
	v_mfma_f32_16x16x32_bf16 v[8:11], v[52:55], v[206:209], 0
	v_mfma_f32_16x16x32_bf16 v[4:7], v[60:63], v[206:209], 0
	v_mfma_f32_16x16x32_bf16 v[28:31], v[56:59], v[168:171], v[28:31]
	v_mfma_f32_16x16x32_bf16 v[32:35], v[64:67], v[168:171], v[32:35]
	v_mfma_f32_16x16x32_bf16 v[20:23], v[56:59], v[188:191], v[20:23]
	v_mfma_f32_16x16x32_bf16 v[24:27], v[64:67], v[188:191], v[24:27]
	v_mfma_f32_16x16x32_bf16 v[16:19], v[56:59], v[202:205], v[16:19]
	v_mfma_f32_16x16x32_bf16 v[12:15], v[64:67], v[202:205], v[12:15]
	v_mfma_f32_16x16x32_bf16 v[8:11], v[56:59], v[210:213], v[8:11]
	v_mfma_f32_16x16x32_bf16 v[4:7], v[64:67], v[210:213], v[4:7]
	s_setprio 0
	s_barrier
	s_branch .Lpe_join_108
	.p2align	8

; template <class Epi, class Sched, bool ALIGN_EPI = false, bool SP2 = false, bool ACHUNK = false>
; __device__ __forceinline__ void gemm_phase(PG8_LAS unsigned char* lds, const Gemm g, const Sched& S, const Epi& E) {
;     ...
;         const bool has_next = S.next(ui + 1, nxt);
;         const char* nA = has_next ? (const char*)g.A + (size_t)nxt.pm * tstepA : cA; const char* nB = has_next ? (const char*)g.Bt + (size_t)nxt.pn * tstepB : cB;
;         for (int t = 0; t < nt; t += 2) {
;             const bool last = (t == nt - 2);
;             if constexpr (Epi::HAS_MID) { if (t == Epi::MID_T) E.mid(acc, cur, wr, wc, fr, fq, ShflDev{}); }
;             const char* a1 = cA + (size_t)(t + 1) * kstep;
;             const char* a2 = last ? nA : cA + (size_t)(t + 2) * kstep; const char* b2 = last ? nB : cB + (size_t)(t + 2) * kstep;
;             const char* a3 = a2 + kstep; const char* b3 = b2 + kstep;
.LBB0_215:
	s_add_u32 s48, s20, 0x100
	s_addc_u32 s49, s21, 0
	s_add_u32 s20, s22, 0x80
	s_addc_u32 s21, s23, 0
	s_mov_b32 s22, 0
	.p2align	8

.LBB0_267:
	v_mov_b32_e32 v2, v232
	v_mov_b32_e32 v4, v233
	s_mov_b32 s9, 0x8000
	v_lshl_add_u32 v4, v4, 3, s47
	v_add_u32_e32 v134, s48, v2
	v_ashrrev_i32_e32 v5, 31, v4
	v_ashrrev_i32_e32 v135, 31, v134
	v_lshl_add_u64 v[4:5], v[4:5], 1, s[76:77]
	v_lshlrev_b64 v[134:135], 11, v[134:135]
	v_lshl_add_u64 v[4:5], v[4:5], 0, v[134:135]
	global_load_dwordx4 v[214:217], v[4:5], off
	global_load_dwordx4 v[190:193], v[4:5], off offset:256
	v_add_co_u32_e32 v136, vcc, s9, v4
	s_mov_b64 s[52:53], 0x8000
	s_nop 0
	v_addc_co_u32_e32 v137, vcc, 0, v5, vcc
	v_lshl_add_u64 v[134:135], v[4:5], 0, s[52:53]
	global_load_dwordx4 v[186:189], v[136:137], off
	global_load_dwordx4 v[182:185], v[134:135], off offset:256
	s_mov_b32 s9, 0x10000
	v_add_co_u32_e32 v136, vcc, s9, v4
	s_mov_b64 s[52:53], 0x10000
	s_nop 0
	v_addc_co_u32_e32 v137, vcc, 0, v5, vcc
	v_lshl_add_u64 v[134:135], v[4:5], 0, s[52:53]
	global_load_dwordx4 v[178:181], v[136:137], off
	global_load_dwordx4 v[174:177], v[134:135], off offset:256
	s_mov_b32 s9, 0x18000
	v_add_co_u32_e32 v136, vcc, s9, v4
	s_mov_b64 s[52:53], 0x18000
	s_nop 0
	v_addc_co_u32_e32 v137, vcc, 0, v5, vcc
	v_lshl_add_u64 v[134:135], v[4:5], 0, s[52:53]
	global_load_dwordx4 v[170:173], v[136:137], off
	global_load_dwordx4 v[166:169], v[134:135], off offset:256
	s_mov_b32 s9, 0x40000
	v_add_co_u32_e32 v136, vcc, s9, v4
	s_mov_b64 s[52:53], 0x40000
	s_nop 0
	v_addc_co_u32_e32 v137, vcc, 0, v5, vcc
	v_lshl_add_u64 v[134:135], v[4:5], 0, s[52:53]
	global_load_dwordx4 v[162:165], v[136:137], off
	global_load_dwordx4 v[158:161], v[134:135], off offset:256
	s_mov_b32 s9, 0x48000
	v_add_co_u32_e32 v136, vcc, s9, v4
	s_mov_b64 s[52:53], 0x48000
	s_nop 0
	v_addc_co_u32_e32 v137, vcc, 0, v5, vcc
	v_lshl_add_u64 v[134:135], v[4:5], 0, s[52:53]
	global_load_dwordx4 v[154:157], v[136:137], off
	global_load_dwordx4 v[142:145], v[134:135], off offset:256
	s_mov_b32 s9, 0x50000
	s_mov_b64 s[52:53], 0x50000
	v_add_co_u32_e32 v136, vcc, s9, v4
	v_lshl_add_u64 v[134:135], v[4:5], 0, s[52:53]
	s_nop 0
	v_addc_co_u32_e32 v137, vcc, 0, v5, vcc
	global_load_dwordx4 v[146:149], v[136:137], off
	s_nop 0
	global_load_dwordx4 v[134:137], v[134:135], off offset:256
	s_mov_b64 s[52:53], 0x58000
	s_mov_b32 s9, 0x58000
	v_lshl_add_u64 v[138:139], v[4:5], 0, s[52:53]
	v_add_co_u32_e32 v4, vcc, s9, v4
	s_nop 1
	v_addc_co_u32_e32 v5, vcc, 0, v5, vcc
	global_load_dwordx4 v[150:153], v[4:5], off
	s_nop 0
	global_load_dwordx4 v[138:141], v[138:139], off offset:256
	s_waitcnt vmcnt(0)
	v_lshlrev_b32_e32 v4, 16, v214
	v_and_b32_e32 v5, 0xffff0000, v214
	v_pk_mul_f32 v[126:127], v[126:127], v[4:5]
	v_lshlrev_b32_e32 v4, 16, v216
	v_and_b32_e32 v5, 0xffff0000, v216
	v_pk_mul_f32 v[130:131], v[130:131], v[4:5]
	v_lshlrev_b32_e32 v4, 16, v190
	v_and_b32_e32 v5, 0xffff0000, v190
	v_pk_mul_f32 v[122:123], v[122:123], v[4:5]
	v_lshlrev_b32_e32 v4, 16, v192
	v_and_b32_e32 v5, 0xffff0000, v192
	v_pk_mul_f32 v[118:119], v[118:119], v[4:5]
	v_lshlrev_b32_e32 v4, 16, v186
	v_and_b32_e32 v5, 0xffff0000, v186
	v_pk_mul_f32 v[114:115], v[114:115], v[4:5]
	v_lshlrev_b32_e32 v4, 16, v188
	v_and_b32_e32 v5, 0xffff0000, v188
	v_pk_mul_f32 v[110:111], v[110:111], v[4:5]
	v_lshlrev_b32_e32 v4, 16, v182
	v_and_b32_e32 v5, 0xffff0000, v182
	v_pk_mul_f32 v[106:107], v[106:107], v[4:5]
	v_lshlrev_b32_e32 v4, 16, v184
	v_and_b32_e32 v5, 0xffff0000, v184
	v_pk_mul_f32 v[102:103], v[102:103], v[4:5]
	v_lshlrev_b32_e32 v4, 16, v178
	v_and_b32_e32 v5, 0xffff0000, v178
	v_pk_mul_f32 v[98:99], v[98:99], v[4:5]
	v_lshlrev_b32_e32 v4, 16, v180
	v_and_b32_e32 v5, 0xffff0000, v180
	v_pk_mul_f32 v[94:95], v[94:95], v[4:5]
	v_lshlrev_b32_e32 v4, 16, v174
	v_and_b32_e32 v5, 0xffff0000, v174
	v_pk_mul_f32 v[90:91], v[90:91], v[4:5]
	v_lshlrev_b32_e32 v4, 16, v176
	v_and_b32_e32 v5, 0xffff0000, v176
	v_pk_mul_f32 v[86:87], v[86:87], v[4:5]
	v_lshlrev_b32_e32 v4, 16, v170
	v_and_b32_e32 v5, 0xffff0000, v170
	v_pk_mul_f32 v[82:83], v[82:83], v[4:5]
	v_lshlrev_b32_e32 v4, 16, v172
	v_and_b32_e32 v5, 0xffff0000, v172
	v_pk_mul_f32 v[78:79], v[78:79], v[4:5]
	v_lshlrev_b32_e32 v4, 16, v166
	v_and_b32_e32 v5, 0xffff0000, v166
	v_pk_mul_f32 v[74:75], v[74:75], v[4:5]
	v_lshlrev_b32_e32 v4, 16, v168
	v_and_b32_e32 v5, 0xffff0000, v168
	v_pk_mul_f32 v[70:71], v[70:71], v[4:5]
	v_lshlrev_b32_e32 v4, 16, v162
	v_and_b32_e32 v5, 0xffff0000, v162
	v_pk_mul_f32 v[66:67], v[66:67], v[4:5]
	v_lshlrev_b32_e32 v4, 16, v164
	v_and_b32_e32 v5, 0xffff0000, v164
	v_pk_mul_f32 v[62:63], v[62:63], v[4:5]
	v_lshlrev_b32_e32 v4, 16, v158
	v_and_b32_e32 v5, 0xffff0000, v158
	v_pk_mul_f32 v[58:59], v[58:59], v[4:5]
	v_lshlrev_b32_e32 v4, 16, v160
	v_and_b32_e32 v5, 0xffff0000, v160
	v_pk_mul_f32 v[54:55], v[54:55], v[4:5]
	v_lshlrev_b32_e32 v4, 16, v154
	v_and_b32_e32 v5, 0xffff0000, v154
	v_pk_mul_f32 v[50:51], v[50:51], v[4:5]
	v_lshlrev_b32_e32 v4, 16, v156
	v_and_b32_e32 v5, 0xffff0000, v156
	v_pk_mul_f32 v[46:47], v[46:47], v[4:5]
	v_lshlrev_b32_e32 v4, 16, v142
	v_and_b32_e32 v5, 0xffff0000, v142
	v_pk_mul_f32 v[42:43], v[42:43], v[4:5]
	v_lshlrev_b32_e32 v4, 16, v144
	v_and_b32_e32 v5, 0xffff0000, v144
	v_pk_mul_f32 v[38:39], v[38:39], v[4:5]
	v_lshlrev_b32_e32 v4, 16, v146
	v_and_b32_e32 v5, 0xffff0000, v146
	v_pk_mul_f32 v[34:35], v[34:35], v[4:5]
	v_lshlrev_b32_e32 v4, 16, v148
	v_and_b32_e32 v5, 0xffff0000, v148
	v_pk_mul_f32 v[30:31], v[30:31], v[4:5]
	v_lshlrev_b32_e32 v4, 16, v134
	v_and_b32_e32 v5, 0xffff0000, v134
	v_lshlrev_b32_e32 v134, 16, v135
	v_and_b32_e32 v135, 0xffff0000, v135
	v_pk_mul_f32 v[28:29], v[28:29], v[134:135]
	v_pk_mul_f32 v[26:27], v[26:27], v[4:5]
	v_lshlrev_b32_e32 v4, 16, v136
	v_and_b32_e32 v5, 0xffff0000, v136
	v_lshlrev_b32_e32 v134, 16, v137
	v_and_b32_e32 v135, 0xffff0000, v137
	v_lshlrev_b32_e32 v142, 16, v143
	v_and_b32_e32 v143, 0xffff0000, v143
	v_pk_mul_f32 v[24:25], v[24:25], v[134:135]
	v_pk_mul_f32 v[22:23], v[22:23], v[4:5]
	v_lshlrev_b32_e32 v4, 16, v150
	v_and_b32_e32 v5, 0xffff0000, v150
	v_lshlrev_b32_e32 v134, 16, v151
	v_and_b32_e32 v135, 0xffff0000, v151
	v_pk_mul_f32 v[44:45], v[44:45], v[142:143]
	v_lshlrev_b32_e32 v142, 16, v145
	v_and_b32_e32 v143, 0xffff0000, v145
	v_pk_mul_f32 v[20:21], v[20:21], v[134:135]
	v_pk_mul_f32 v[18:19], v[18:19], v[4:5]
	v_lshlrev_b32_e32 v4, 16, v152
	v_and_b32_e32 v5, 0xffff0000, v152
	v_lshlrev_b32_e32 v134, 16, v153
	v_and_b32_e32 v135, 0xffff0000, v153
	v_lshlrev_b32_e32 v214, 16, v215
	v_and_b32_e32 v215, 0xffff0000, v215
	v_lshlrev_b32_e32 v190, 16, v191
	v_and_b32_e32 v191, 0xffff0000, v191
	v_lshlrev_b32_e32 v186, 16, v187
	v_and_b32_e32 v187, 0xffff0000, v187
	v_lshlrev_b32_e32 v182, 16, v183
	v_and_b32_e32 v183, 0xffff0000, v183
	v_lshlrev_b32_e32 v178, 16, v179
	v_and_b32_e32 v179, 0xffff0000, v179
	v_lshlrev_b32_e32 v174, 16, v175
	v_and_b32_e32 v175, 0xffff0000, v175
	v_lshlrev_b32_e32 v170, 16, v171
	v_and_b32_e32 v171, 0xffff0000, v171
	v_lshlrev_b32_e32 v166, 16, v167
	v_and_b32_e32 v167, 0xffff0000, v167
	v_lshlrev_b32_e32 v162, 16, v163
	v_and_b32_e32 v163, 0xffff0000, v163
	v_lshlrev_b32_e32 v158, 16, v159
	v_and_b32_e32 v159, 0xffff0000, v159
	v_lshlrev_b32_e32 v154, 16, v155
	v_and_b32_e32 v155, 0xffff0000, v155
	v_pk_mul_f32 v[40:41], v[40:41], v[142:143]
	v_lshlrev_b32_e32 v142, 16, v147
	v_and_b32_e32 v143, 0xffff0000, v147
	v_pk_mul_f32 v[16:17], v[16:17], v[134:135]
	v_pk_mul_f32 v[14:15], v[14:15], v[4:5]
	v_lshlrev_b32_e32 v4, 16, v138
	v_and_b32_e32 v5, 0xffff0000, v138
	v_lshlrev_b32_e32 v134, 16, v139
	v_and_b32_e32 v135, 0xffff0000, v139
	v_pk_mul_f32 v[128:129], v[128:129], v[214:215]
	v_lshlrev_b32_e32 v214, 16, v217
	v_and_b32_e32 v215, 0xffff0000, v217
	v_pk_mul_f32 v[124:125], v[124:125], v[190:191]
	v_lshlrev_b32_e32 v190, 16, v193
	v_and_b32_e32 v191, 0xffff0000, v193
	v_pk_mul_f32 v[116:117], v[116:117], v[186:187]
	v_lshlrev_b32_e32 v186, 16, v189
	v_and_b32_e32 v187, 0xffff0000, v189
	v_pk_mul_f32 v[108:109], v[108:109], v[182:183]
	v_lshlrev_b32_e32 v182, 16, v185
	v_and_b32_e32 v183, 0xffff0000, v185
	v_pk_mul_f32 v[100:101], v[100:101], v[178:179]
	v_lshlrev_b32_e32 v178, 16, v181
	v_and_b32_e32 v179, 0xffff0000, v181
	v_pk_mul_f32 v[92:93], v[92:93], v[174:175]
	v_lshlrev_b32_e32 v174, 16, v177
	v_and_b32_e32 v175, 0xffff0000, v177
	v_pk_mul_f32 v[84:85], v[84:85], v[170:171]
	v_lshlrev_b32_e32 v170, 16, v173
	v_and_b32_e32 v171, 0xffff0000, v173
	v_pk_mul_f32 v[76:77], v[76:77], v[166:167]
	v_lshlrev_b32_e32 v166, 16, v169
	v_and_b32_e32 v167, 0xffff0000, v169
	v_pk_mul_f32 v[68:69], v[68:69], v[162:163]
	v_lshlrev_b32_e32 v162, 16, v165
	v_and_b32_e32 v163, 0xffff0000, v165
	v_pk_mul_f32 v[60:61], v[60:61], v[158:159]
	v_lshlrev_b32_e32 v158, 16, v161
	v_and_b32_e32 v159, 0xffff0000, v161
	v_pk_mul_f32 v[52:53], v[52:53], v[154:155]
	v_lshlrev_b32_e32 v154, 16, v157
	v_and_b32_e32 v155, 0xffff0000, v157
	v_pk_mul_f32 v[36:37], v[36:37], v[142:143]
	v_lshlrev_b32_e32 v142, 16, v149
	v_and_b32_e32 v143, 0xffff0000, v149
	v_pk_mul_f32 v[12:13], v[12:13], v[134:135]
	v_pk_mul_f32 v[10:11], v[10:11], v[4:5]
	v_lshlrev_b32_e32 v4, 16, v140
	v_and_b32_e32 v5, 0xffff0000, v140
	v_lshlrev_b32_e32 v134, 16, v141
	v_and_b32_e32 v135, 0xffff0000, v141
	v_pk_mul_f32 v[132:133], v[132:133], v[214:215]
	v_pk_mul_f32 v[120:121], v[120:121], v[190:191]
	v_pk_mul_f32 v[112:113], v[112:113], v[186:187]
	v_pk_mul_f32 v[104:105], v[104:105], v[182:183]
	v_pk_mul_f32 v[96:97], v[96:97], v[178:179]
	v_pk_mul_f32 v[88:89], v[88:89], v[174:175]
	v_pk_mul_f32 v[80:81], v[80:81], v[170:171]
	v_pk_mul_f32 v[72:73], v[72:73], v[166:167]
	v_pk_mul_f32 v[64:65], v[64:65], v[162:163]
	v_pk_mul_f32 v[56:57], v[56:57], v[158:159]
	v_pk_mul_f32 v[48:49], v[48:49], v[154:155]
	v_pk_mul_f32 v[32:33], v[32:33], v[142:143]
	v_pk_mul_f32 v[8:9], v[8:9], v[134:135]
	v_pk_mul_f32 v[6:7], v[6:7], v[4:5]
	.p2align	8

; #define PG8_STAGE(bufoff, gbase, voff) do { _Pragma("unroll") for (int _i = 0; _i < 2; ++_i) \
;         __builtin_amdgcn_global_load_lds((const unsigned*)((const char*)(gbase) + (voff)[_i]), (PG8_LAS unsigned*)(lds + (bufoff) + ldsw + _i * 8192), 16, 0, 0); } while (0)
; #define PG8_LDA(dst, b, h) do { _Pragma("unroll") for (int m = 0; m < 4; ++m) _Pragma("unroll") for (int k = 0; k < 2; ++k) dst[m][k] = *(const PG8_LAS bf16x8*)(lds + PG8_SA(b, h) + aoff + m * 2048 + k * 1024); } while (0)
; #define PG8_LDB(dst, b, h) do { _Pragma("unroll") for (int n = 0; n < 2; ++n) _Pragma("unroll") for (int k = 0; k < 2; ++k) dst[n][k] = *(const PG8_LAS bf16x8*)(lds + PG8_SB(b, h) + boff + n * 2048 + k * 1024); } while (0)
; #define PG8_MMA(ai, bj, At, Bt) do { __builtin_amdgcn_s_setprio(1); _Pragma("unroll") for (int m = 0; m < 4; ++m) _Pragma("unroll") for (int n = 0; n < 2; ++n) _Pragma("unroll") for (int k = 0; k < 2; ++k) \
;         acc[ai][bj][m][n] = __builtin_amdgcn_mfma_f32_16x16x32_bf16(Bt[n][k], At[m][k], acc[ai][bj][m][n], 0, 0, 0); __builtin_amdgcn_s_setprio(0); } while (0)
; #define PG8_WAIT_V(n) asm volatile("s_waitcnt vmcnt(" #n ")" ::: "memory")
; #define PG8_WAIT_L(n) asm volatile("s_waitcnt lgkmcnt(" #n ")" ::: "memory")
; #define PG8_BAR __builtin_amdgcn_s_barrier()
; template <class Epi, class Sched, bool ALIGN_EPI = false, bool SP2 = false, bool ACHUNK = false>
; __device__ __forceinline__ void gemm_phase(PG8_LAS unsigned char* lds, const Gemm g, const Sched& S, const Epi& E) {
;     ...
;             const char* a1 = cA + (size_t)(t + 1) * kstep;
;             const char* a2 = last ? nA : cA + (size_t)(t + 2) * kstep; const char* b2 = last ? nB : cB + (size_t)(t + 2) * kstep;
;             const char* a3 = a2 + kstep; const char* b3 = b2 + kstep;
;             if (last && has_next) S.a_ready(nxt);
;             if constexpr (SP2) {
;             PG8_LDB(B0, 0, 0); PG8_LDB(B1, 0, 1); PG8_SCHED; PG8_LDA(At, 0, 0); PG8_STAGE(PG8_SA(1, 1), a1 + hstepA, voffA);
;             PG8_WAIT_V(8); PG8_WAIT_L(0); PG8_BAR; PG8_MMA(0, 0, At, B0); PG8_MMA(0, 1, At, B1); PG8_BAR; PG8_SCHED;
;             PG8_LDA(At, 0, 1); PG8_STAGE(PG8_SB(0, 0), b2, voffB); PG8_STAGE(PG8_SB(0, 1), b2 + hstepB, voffB); PG8_STAGE(PG8_SA(0, 0), a2, voffA);
;             PG8_WAIT_V(8); PG8_WAIT_L(0); PG8_BAR; PG8_MMA(1, 0, At, B0); PG8_MMA(1, 1, At, B1); PG8_BAR; PG8_SCHED;
.LBB0_351:
	s_andn2_b64 vcc, exec, s[4:5]
	s_cbranch_vccnz .LBB0_342
	s_add_u32 s40, s18, 0x100
	s_addc_u32 s41, s19, 0
	s_add_u32 s18, s20, 0x80
	s_addc_u32 s19, s21, 0
	s_mov_b32 s20, 0
	s_add_i32 s42, s20, 2
	s_add_u32 s43, s18, 0x80
	s_addc_u32 s21, s19, 0
	s_add_i32 s46, 0, 0x10000
	s_cmp_eq_u32 s33, s20
	s_cselect_b32 s21, s13, s21
	s_cselect_b32 s20, s12, s43
	v_add_u32_e32 v153, s46, v143
	s_cselect_b32 s45, s17, s41
	s_cselect_b32 s44, s16, s40
	s_add_i32 s43, 0, 0x14000
	ds_read_b128 v[154:157], v153
	ds_read_b128 v[158:161], v153 offset:1024
	ds_read_b128 v[162:165], v153 offset:2048
	ds_read_b128 v[166:169], v153 offset:3072
	v_add_u32_e32 v153, s43, v143
	ds_read_b128 v[170:173], v153
	ds_read_b128 v[174:177], v153 offset:1024
	ds_read_b128 v[178:181], v153 offset:2048
	ds_read_b128 v[182:185], v153 offset:3072
	s_add_i32 m0, s25, 0xc000
	ds_read_b128 v[186:189], v152
	ds_read_b128 v[190:193], v152 offset:1024
	ds_read_b128 v[198:201], v152 offset:2048
	ds_read_b128 v[202:205], v152 offset:3072
	ds_read_b128 v[206:209], v152 offset:4096
	ds_read_b128 v[210:213], v152 offset:5120
	ds_read_b128 v[214:217], v152 offset:6144
	ds_read_b128 v[218:221], v152 offset:7168
	global_load_lds_dwordx4 v138, s[18:19]
	s_add_i32 m0, s25, 0xe000
	s_nop 0
	global_load_lds_dwordx4 v140, s[18:19]
	s_waitcnt vmcnt(8)
	s_waitcnt lgkmcnt(0)
	s_barrier
	s_setprio 1
	v_mfma_f32_16x16x32_bf16 v[124:127], v[154:157], v[186:189], 0
	v_mfma_f32_16x16x32_bf16 v[128:131], v[162:165], v[186:189], 0
	v_mfma_f32_16x16x32_bf16 v[112:115], v[154:157], v[198:201], 0
	v_mfma_f32_16x16x32_bf16 v[108:111], v[162:165], v[198:201], 0
	v_mfma_f32_16x16x32_bf16 v[96:99], v[154:157], v[206:209], 0
	v_mfma_f32_16x16x32_bf16 v[92:95], v[162:165], v[206:209], 0
	v_mfma_f32_16x16x32_bf16 v[80:83], v[154:157], v[214:217], 0
	v_mfma_f32_16x16x32_bf16 v[76:79], v[162:165], v[214:217], 0
	v_mfma_f32_16x16x32_bf16 v[124:127], v[158:161], v[190:193], v[124:127]
	v_mfma_f32_16x16x32_bf16 v[128:131], v[166:169], v[190:193], v[128:131]
	v_mfma_f32_16x16x32_bf16 v[112:115], v[158:161], v[202:205], v[112:115]
	v_mfma_f32_16x16x32_bf16 v[108:111], v[166:169], v[202:205], v[108:111]
	v_mfma_f32_16x16x32_bf16 v[96:99], v[158:161], v[210:213], v[96:99]
	v_mfma_f32_16x16x32_bf16 v[92:95], v[166:169], v[210:213], v[92:95]
	v_mfma_f32_16x16x32_bf16 v[80:83], v[158:161], v[218:221], v[80:83]
	v_mfma_f32_16x16x32_bf16 v[76:79], v[166:169], v[218:221], v[76:79]
	s_setprio 0
	s_setprio 1
	v_mfma_f32_16x16x32_bf16 v[120:123], v[170:173], v[186:189], 0
	v_mfma_f32_16x16x32_bf16 v[116:119], v[178:181], v[186:189], 0
	v_mfma_f32_16x16x32_bf16 v[104:107], v[170:173], v[198:201], 0
	v_mfma_f32_16x16x32_bf16 v[100:103], v[178:181], v[198:201], 0
	v_mfma_f32_16x16x32_bf16 v[88:91], v[170:173], v[206:209], 0
	v_mfma_f32_16x16x32_bf16 v[84:87], v[178:181], v[206:209], 0
	v_mfma_f32_16x16x32_bf16 v[72:75], v[170:173], v[214:217], 0
	v_mfma_f32_16x16x32_bf16 v[68:71], v[178:181], v[214:217], 0
	v_mfma_f32_16x16x32_bf16 v[120:123], v[174:177], v[190:193], v[120:123]
	v_mfma_f32_16x16x32_bf16 v[116:119], v[182:185], v[190:193], v[116:119]
	v_mfma_f32_16x16x32_bf16 v[104:107], v[174:177], v[202:205], v[104:107]
	v_mfma_f32_16x16x32_bf16 v[100:103], v[182:185], v[202:205], v[100:103]
	v_mfma_f32_16x16x32_bf16 v[88:91], v[174:177], v[210:213], v[88:91]
	v_mfma_f32_16x16x32_bf16 v[84:87], v[182:185], v[210:213], v[84:87]
	v_mfma_f32_16x16x32_bf16 v[72:75], v[174:177], v[218:221], v[72:75]
	v_mfma_f32_16x16x32_bf16 v[68:71], v[182:185], v[218:221], v[68:71]
	s_setprio 0
	s_barrier
	s_add_i32 s46, s46, s24
	s_mov_b32 m0, s46
	ds_read_b128 v[186:189], v152 offset:16384
	ds_read_b128 v[190:193], v152 offset:17408
	ds_read_b128 v[198:201], v152 offset:18432
	ds_read_b128 v[202:205], v152 offset:19456
	ds_read_b128 v[206:209], v152 offset:20480
	ds_read_b128 v[210:213], v152 offset:21504
	ds_read_b128 v[214:217], v152 offset:22528
	ds_read_b128 v[218:221], v152 offset:23552
	global_load_lds_dwordx4 v2, s[44:45]
	s_add_i32 m0, s46, 0x2000
	s_add_i32 s43, s43, s24
	global_load_lds_dwordx4 v136, s[44:45]
	s_add_u32 s44, s44, s0
	s_addc_u32 s45, s45, s1
	s_mov_b64 vcc, s[44:45]
	s_sub_u32 s98, s44, s0
	s_subb_u32 s99, s45, s1
	s_mov_b32 m0, s43
	s_nop 0
	global_load_lds_dwordx4 v2, s[44:45]
	s_add_i32 m0, s43, 0x2000
	s_nop 0
	global_load_lds_dwordx4 v136, s[44:45]
	s_mov_b32 m0, s25
	s_nop 0
	global_load_lds_dwordx4 v132, s[20:21]
	s_mov_b32 m0, s26
	s_nop 0
	global_load_lds_dwordx4 v134, s[20:21]
	s_waitcnt vmcnt(8)
	s_waitcnt lgkmcnt(0)
	s_barrier
	s_setprio 1
	v_mfma_f32_16x16x32_bf16 v[64:67], v[154:157], v[186:189], 0
	v_mfma_f32_16x16x32_bf16 v[60:63], v[162:165], v[186:189], 0
	v_mfma_f32_16x16x32_bf16 v[48:51], v[154:157], v[198:201], 0
	v_mfma_f32_16x16x32_bf16 v[44:47], v[162:165], v[198:201], 0
	v_mfma_f32_16x16x32_bf16 v[32:35], v[154:157], v[206:209], 0
	v_mfma_f32_16x16x32_bf16 v[28:31], v[162:165], v[206:209], 0
	v_mfma_f32_16x16x32_bf16 v[16:19], v[154:157], v[214:217], 0
	v_mfma_f32_16x16x32_bf16 v[12:15], v[162:165], v[214:217], 0
	v_mfma_f32_16x16x32_bf16 v[64:67], v[158:161], v[190:193], v[64:67]
	v_mfma_f32_16x16x32_bf16 v[60:63], v[166:169], v[190:193], v[60:63]
	v_mfma_f32_16x16x32_bf16 v[48:51], v[158:161], v[202:205], v[48:51]
	v_mfma_f32_16x16x32_bf16 v[44:47], v[166:169], v[202:205], v[44:47]
	v_mfma_f32_16x16x32_bf16 v[32:35], v[158:161], v[210:213], v[32:35]
	v_mfma_f32_16x16x32_bf16 v[28:31], v[166:169], v[210:213], v[28:31]
	v_mfma_f32_16x16x32_bf16 v[16:19], v[158:161], v[218:221], v[16:19]
	v_mfma_f32_16x16x32_bf16 v[12:15], v[166:169], v[218:221], v[12:15]
	s_setprio 0
	s_setprio 1
	v_mfma_f32_16x16x32_bf16 v[56:59], v[170:173], v[186:189], 0
	v_mfma_f32_16x16x32_bf16 v[52:55], v[178:181], v[186:189], 0
	v_mfma_f32_16x16x32_bf16 v[40:43], v[170:173], v[198:201], 0
	v_mfma_f32_16x16x32_bf16 v[36:39], v[178:181], v[198:201], 0
	v_mfma_f32_16x16x32_bf16 v[24:27], v[170:173], v[206:209], 0
	v_mfma_f32_16x16x32_bf16 v[20:23], v[178:181], v[206:209], 0
	v_mfma_f32_16x16x32_bf16 v[8:11], v[170:173], v[214:217], 0
	v_mfma_f32_16x16x32_bf16 v[4:7], v[178:181], v[214:217], 0
	v_mfma_f32_16x16x32_bf16 v[56:59], v[174:177], v[190:193], v[56:59]
	v_mfma_f32_16x16x32_bf16 v[52:55], v[182:185], v[190:193], v[52:55]
	v_mfma_f32_16x16x32_bf16 v[40:43], v[174:177], v[202:205], v[40:43]
	v_mfma_f32_16x16x32_bf16 v[36:39], v[182:185], v[202:205], v[36:39]
	v_mfma_f32_16x16x32_bf16 v[24:27], v[174:177], v[210:213], v[24:27]
	v_mfma_f32_16x16x32_bf16 v[20:23], v[182:185], v[210:213], v[20:23]
	v_mfma_f32_16x16x32_bf16 v[8:11], v[174:177], v[218:221], v[8:11]
	v_mfma_f32_16x16x32_bf16 v[4:7], v[182:185], v[218:221], v[4:7]
	s_setprio 0
	s_barrier
	s_branch .Lpe_join_353
	.p2align	8

; #define PG8_STAGE(bufoff, gbase, voff) do { _Pragma("unroll") for (int _i = 0; _i < 2; ++_i) \
;         __builtin_amdgcn_global_load_lds((const unsigned*)((const char*)(gbase) + (voff)[_i]), (PG8_LAS unsigned*)(lds + (bufoff) + ldsw + _i * 8192), 16, 0, 0); } while (0)
; #define PG8_LDA(dst, b, h) do { _Pragma("unroll") for (int m = 0; m < 4; ++m) _Pragma("unroll") for (int k = 0; k < 2; ++k) dst[m][k] = *(const PG8_LAS bf16x8*)(lds + PG8_SA(b, h) + aoff + m * 2048 + k * 1024); } while (0)
; #define PG8_LDB(dst, b, h) do { _Pragma("unroll") for (int n = 0; n < 2; ++n) _Pragma("unroll") for (int k = 0; k < 2; ++k) dst[n][k] = *(const PG8_LAS bf16x8*)(lds + PG8_SB(b, h) + boff + n * 2048 + k * 1024); } while (0)
; #define PG8_MMA(ai, bj, At, Bt) do { __builtin_amdgcn_s_setprio(1); _Pragma("unroll") for (int m = 0; m < 4; ++m) _Pragma("unroll") for (int n = 0; n < 2; ++n) _Pragma("unroll") for (int k = 0; k < 2; ++k) \
;         acc[ai][bj][m][n] = __builtin_amdgcn_mfma_f32_16x16x32_bf16(Bt[n][k], At[m][k], acc[ai][bj][m][n], 0, 0, 0); __builtin_amdgcn_s_setprio(0); } while (0)
; #define PG8_WAIT_V(n) asm volatile("s_waitcnt vmcnt(" #n ")" ::: "memory")
; #define PG8_WAIT_L(n) asm volatile("s_waitcnt lgkmcnt(" #n ")" ::: "memory")
; #define PG8_BAR __builtin_amdgcn_s_barrier()
; template <class Epi, class Sched, bool ALIGN_EPI = false, bool SP2 = false, bool ACHUNK = false>
; __device__ __forceinline__ void gemm_phase(PG8_LAS unsigned char* lds, const Gemm g, const Sched& S, const Epi& E) {
;     ...
;             const char* a1 = cA + (size_t)(t + 1) * kstep;
;             const char* a2 = last ? nA : cA + (size_t)(t + 2) * kstep; const char* b2 = last ? nB : cB + (size_t)(t + 2) * kstep;
;             const char* a3 = a2 + kstep; const char* b3 = b2 + kstep;
;             if (last && has_next) S.a_ready(nxt);
;             if constexpr (SP2) {
;             PG8_LDB(B0, 0, 0); PG8_LDB(B1, 0, 1); PG8_SCHED; PG8_LDA(At, 0, 0); PG8_STAGE(PG8_SA(1, 1), a1 + hstepA, voffA);
;             PG8_WAIT_V(8); PG8_WAIT_L(0); PG8_BAR; PG8_MMA(0, 0, At, B0); PG8_MMA(0, 1, At, B1); PG8_BAR; PG8_SCHED;
;             PG8_LDA(At, 0, 1); PG8_STAGE(PG8_SB(0, 0), b2, voffB); PG8_STAGE(PG8_SB(0, 1), b2 + hstepB, voffB); PG8_STAGE(PG8_SA(0, 0), a2, voffA);
;             PG8_WAIT_V(8); PG8_WAIT_L(0); PG8_BAR; PG8_MMA(1, 0, At, B0); PG8_MMA(1, 1, At, B1); PG8_BAR; PG8_SCHED;
.LBB0_375:
	s_andn2_b64 vcc, exec, s[34:35]
	s_cbranch_vccnz .LBB0_379
	s_add_u32 s4, s4, 0x80
	s_addc_u32 s5, s5, 0
	s_add_u32 s8, s6, 0x100
	s_addc_u32 s9, s7, 0
	s_mov_b32 s6, 0
	s_add_i32 s48, s6, 2
	s_add_u32 s49, s4, 0x80
	s_addc_u32 s7, s5, 0
	s_add_i32 s52, 0, 0x10000
	s_cmp_eq_u32 s27, s6
	s_cselect_b32 s7, s1, s7
	s_cselect_b32 s6, s0, s49
	v_add_u32_e32 v2, s52, v175
	s_cselect_b32 s51, s43, s9
	s_cselect_b32 s50, s42, s8
	s_add_i32 s49, 0, 0x14000
	s_waitcnt lgkmcnt(0)
	ds_read_b128 v[146:149], v2
	ds_read_b128 v[150:153], v2 offset:1024
	ds_read_b128 v[154:157], v2 offset:2048
	ds_read_b128 v[158:161], v2 offset:3072
	v_add_u32_e32 v2, s49, v175
	ds_read_b128 v[162:165], v2
	ds_read_b128 v[166:169], v2 offset:1024
	ds_read_b128 v[170:173], v2 offset:2048
	ds_read_b128 v[180:183], v2 offset:3072
	s_add_i32 m0, s20, 0xc000
	ds_read_b128 v[184:187], v179
	ds_read_b128 v[188:191], v179 offset:1024
	ds_read_b128 v[198:201], v179 offset:2048
	ds_read_b128 v[202:205], v179 offset:3072
	ds_read_b128 v[206:209], v179 offset:4096
	ds_read_b128 v[210:213], v179 offset:5120
	ds_read_b128 v[214:217], v179 offset:6144
	ds_read_b128 v[218:221], v179 offset:7168
	global_load_lds_dwordx4 v142, s[4:5]
	s_add_i32 m0, s20, 0xe000
	s_nop 0
	global_load_lds_dwordx4 v144, s[4:5]
	s_waitcnt vmcnt(8)
	s_waitcnt lgkmcnt(0)
	s_barrier
	s_setprio 1
	v_mfma_f32_16x16x32_bf16 v[124:127], v[146:149], v[184:187], 0
	v_mfma_f32_16x16x32_bf16 v[116:119], v[154:157], v[184:187], 0
	v_mfma_f32_16x16x32_bf16 v[108:111], v[146:149], v[198:201], 0
	v_mfma_f32_16x16x32_bf16 v[100:103], v[154:157], v[198:201], 0
	v_mfma_f32_16x16x32_bf16 v[92:95], v[146:149], v[206:209], 0
	v_mfma_f32_16x16x32_bf16 v[84:87], v[154:157], v[206:209], 0
	v_mfma_f32_16x16x32_bf16 v[76:79], v[146:149], v[214:217], 0
	v_mfma_f32_16x16x32_bf16 v[68:71], v[154:157], v[214:217], 0
	v_mfma_f32_16x16x32_bf16 v[124:127], v[150:153], v[188:191], v[124:127]
	v_mfma_f32_16x16x32_bf16 v[116:119], v[158:161], v[188:191], v[116:119]
	v_mfma_f32_16x16x32_bf16 v[108:111], v[150:153], v[202:205], v[108:111]
	v_mfma_f32_16x16x32_bf16 v[100:103], v[158:161], v[202:205], v[100:103]
	v_mfma_f32_16x16x32_bf16 v[92:95], v[150:153], v[210:213], v[92:95]
	v_mfma_f32_16x16x32_bf16 v[84:87], v[158:161], v[210:213], v[84:87]
	v_mfma_f32_16x16x32_bf16 v[76:79], v[150:153], v[218:221], v[76:79]
	v_mfma_f32_16x16x32_bf16 v[68:71], v[158:161], v[218:221], v[68:71]
	s_setprio 0
	s_setprio 1
	v_mfma_f32_16x16x32_bf16 v[128:131], v[162:165], v[184:187], 0
	v_mfma_f32_16x16x32_bf16 v[120:123], v[170:173], v[184:187], 0
	v_mfma_f32_16x16x32_bf16 v[112:115], v[162:165], v[198:201], 0
	v_mfma_f32_16x16x32_bf16 v[104:107], v[170:173], v[198:201], 0
	v_mfma_f32_16x16x32_bf16 v[96:99], v[162:165], v[206:209], 0
	v_mfma_f32_16x16x32_bf16 v[88:91], v[170:173], v[206:209], 0
	v_mfma_f32_16x16x32_bf16 v[80:83], v[162:165], v[214:217], 0
	v_mfma_f32_16x16x32_bf16 v[72:75], v[170:173], v[214:217], 0
	v_mfma_f32_16x16x32_bf16 v[128:131], v[166:169], v[188:191], v[128:131]
	v_mfma_f32_16x16x32_bf16 v[120:123], v[180:183], v[188:191], v[120:123]
	v_mfma_f32_16x16x32_bf16 v[112:115], v[166:169], v[202:205], v[112:115]
	v_mfma_f32_16x16x32_bf16 v[104:107], v[180:183], v[202:205], v[104:107]
	v_mfma_f32_16x16x32_bf16 v[96:99], v[166:169], v[210:213], v[96:99]
	v_mfma_f32_16x16x32_bf16 v[88:91], v[180:183], v[210:213], v[88:91]
	v_mfma_f32_16x16x32_bf16 v[80:83], v[166:169], v[218:221], v[80:83]
	v_mfma_f32_16x16x32_bf16 v[72:75], v[180:183], v[218:221], v[72:75]
	s_setprio 0
	s_barrier
	s_add_i32 s52, s52, s13
	s_mov_b32 m0, s52
	ds_read_b128 v[184:187], v179 offset:16384
	ds_read_b128 v[188:191], v179 offset:17408
	ds_read_b128 v[198:201], v179 offset:18432
	ds_read_b128 v[202:205], v179 offset:19456
	ds_read_b128 v[206:209], v179 offset:20480
	ds_read_b128 v[210:213], v179 offset:21504
	ds_read_b128 v[214:217], v179 offset:22528
	ds_read_b128 v[218:221], v179 offset:23552
	global_load_lds_dwordx4 v134, s[50:51]
	s_add_i32 m0, s52, 0x2000
	s_add_i32 s49, s49, s13
	global_load_lds_dwordx4 v138, s[50:51]
	s_add_u32 s50, s50, s18
	s_addc_u32 s51, s51, s19
	s_mov_b64 vcc, s[50:51]
	s_sub_u32 s98, s50, s18
	s_subb_u32 s99, s51, s19
	s_mov_b32 m0, s49
	s_nop 0
	global_load_lds_dwordx4 v134, s[50:51]
	s_add_i32 m0, s49, 0x2000
	s_nop 0
	global_load_lds_dwordx4 v138, s[50:51]
	s_mov_b32 m0, s20
	s_nop 0
	global_load_lds_dwordx4 v132, s[6:7]
	s_mov_b32 m0, s21
	s_nop 0
	global_load_lds_dwordx4 v136, s[6:7]
	s_waitcnt vmcnt(8)
	s_waitcnt lgkmcnt(0)
	s_barrier
	s_setprio 1
	v_mfma_f32_16x16x32_bf16 v[60:63], v[146:149], v[184:187], 0
	v_mfma_f32_16x16x32_bf16 v[52:55], v[154:157], v[184:187], 0
	v_mfma_f32_16x16x32_bf16 v[44:47], v[146:149], v[198:201], 0
	v_mfma_f32_16x16x32_bf16 v[36:39], v[154:157], v[198:201], 0
	v_mfma_f32_16x16x32_bf16 v[28:31], v[146:149], v[206:209], 0
	v_mfma_f32_16x16x32_bf16 v[20:23], v[154:157], v[206:209], 0
	v_mfma_f32_16x16x32_bf16 v[12:15], v[146:149], v[214:217], 0
	v_mfma_f32_16x16x32_bf16 v[4:7], v[154:157], v[214:217], 0
	v_mfma_f32_16x16x32_bf16 v[60:63], v[150:153], v[188:191], v[60:63]
	v_mfma_f32_16x16x32_bf16 v[52:55], v[158:161], v[188:191], v[52:55]
	v_mfma_f32_16x16x32_bf16 v[44:47], v[150:153], v[202:205], v[44:47]
	v_mfma_f32_16x16x32_bf16 v[36:39], v[158:161], v[202:205], v[36:39]
	v_mfma_f32_16x16x32_bf16 v[28:31], v[150:153], v[210:213], v[28:31]
	v_mfma_f32_16x16x32_bf16 v[20:23], v[158:161], v[210:213], v[20:23]
	v_mfma_f32_16x16x32_bf16 v[12:15], v[150:153], v[218:221], v[12:15]
	v_mfma_f32_16x16x32_bf16 v[4:7], v[158:161], v[218:221], v[4:7]
	s_setprio 0
	s_setprio 1
	v_mfma_f32_16x16x32_bf16 v[64:67], v[162:165], v[184:187], 0
	v_mfma_f32_16x16x32_bf16 v[56:59], v[170:173], v[184:187], 0
	v_mfma_f32_16x16x32_bf16 v[48:51], v[162:165], v[198:201], 0
	v_mfma_f32_16x16x32_bf16 v[40:43], v[170:173], v[198:201], 0
	v_mfma_f32_16x16x32_bf16 v[32:35], v[162:165], v[206:209], 0
	v_mfma_f32_16x16x32_bf16 v[24:27], v[170:173], v[206:209], 0
	v_mfma_f32_16x16x32_bf16 v[16:19], v[162:165], v[214:217], 0
	v_mfma_f32_16x16x32_bf16 v[8:11], v[170:173], v[214:217], 0
	v_mfma_f32_16x16x32_bf16 v[64:67], v[166:169], v[188:191], v[64:67]
	v_mfma_f32_16x16x32_bf16 v[56:59], v[180:183], v[188:191], v[56:59]
	v_mfma_f32_16x16x32_bf16 v[48:51], v[166:169], v[202:205], v[48:51]
	v_mfma_f32_16x16x32_bf16 v[40:43], v[180:183], v[202:205], v[40:43]
	v_mfma_f32_16x16x32_bf16 v[32:35], v[166:169], v[210:213], v[32:35]
	v_mfma_f32_16x16x32_bf16 v[24:27], v[180:183], v[210:213], v[24:27]
	v_mfma_f32_16x16x32_bf16 v[16:19], v[166:169], v[218:221], v[16:19]
	v_mfma_f32_16x16x32_bf16 v[8:11], v[180:183], v[218:221], v[8:11]
	s_setprio 0
	s_barrier
	s_branch .Lpe_join_377
	.p2align	8

; #define PG8_STAGE(bufoff, gbase, voff) do { _Pragma("unroll") for (int _i = 0; _i < 2; ++_i) \
;         __builtin_amdgcn_global_load_lds((const unsigned*)((const char*)(gbase) + (voff)[_i]), (PG8_LAS unsigned*)(lds + (bufoff) + ldsw + _i * 8192), 16, 0, 0); } while (0)
; #define PG8_LDA(dst, b, h) do { _Pragma("unroll") for (int m = 0; m < 4; ++m) _Pragma("unroll") for (int k = 0; k < 2; ++k) dst[m][k] = *(const PG8_LAS bf16x8*)(lds + PG8_SA(b, h) + aoff + m * 2048 + k * 1024); } while (0)
; #define PG8_LDB(dst, b, h) do { _Pragma("unroll") for (int n = 0; n < 2; ++n) _Pragma("unroll") for (int k = 0; k < 2; ++k) dst[n][k] = *(const PG8_LAS bf16x8*)(lds + PG8_SB(b, h) + boff + n * 2048 + k * 1024); } while (0)
; #define PG8_MMA(ai, bj, At, Bt) do { __builtin_amdgcn_s_setprio(1); _Pragma("unroll") for (int m = 0; m < 4; ++m) _Pragma("unroll") for (int n = 0; n < 2; ++n) _Pragma("unroll") for (int k = 0; k < 2; ++k) \
;         acc[ai][bj][m][n] = __builtin_amdgcn_mfma_f32_16x16x32_bf16(Bt[n][k], At[m][k], acc[ai][bj][m][n], 0, 0, 0); __builtin_amdgcn_s_setprio(0); } while (0)
; #define PG8_WAIT_V(n) asm volatile("s_waitcnt vmcnt(" #n ")" ::: "memory")
; #define PG8_WAIT_L(n) asm volatile("s_waitcnt lgkmcnt(" #n ")" ::: "memory")
; #define PG8_BAR __builtin_amdgcn_s_barrier()
; template <class Epi, class Sched, bool ALIGN_EPI = false, bool SP2 = false, bool ACHUNK = false>
; __device__ __forceinline__ void gemm_phase(PG8_LAS unsigned char* lds, const Gemm g, const Sched& S, const Epi& E) {
;     ...
;             const char* a1 = cA + (size_t)(t + 1) * kstep;
;             const char* a2 = last ? nA : cA + (size_t)(t + 2) * kstep; const char* b2 = last ? nB : cB + (size_t)(t + 2) * kstep;
;             const char* a3 = a2 + kstep; const char* b3 = b2 + kstep;
;             if (last && has_next) S.a_ready(nxt);
;             if constexpr (SP2) {
;             PG8_LDB(B0, 0, 0); PG8_LDB(B1, 0, 1); PG8_SCHED; PG8_LDA(At, 0, 0); PG8_STAGE(PG8_SA(1, 1), a1 + hstepA, voffA);
;             PG8_WAIT_V(8); PG8_WAIT_L(0); PG8_BAR; PG8_MMA(0, 0, At, B0); PG8_MMA(0, 1, At, B1); PG8_BAR; PG8_SCHED;
;             PG8_LDA(At, 0, 1); PG8_STAGE(PG8_SB(0, 0), b2, voffB); PG8_STAGE(PG8_SB(0, 1), b2 + hstepB, voffB); PG8_STAGE(PG8_SA(0, 0), a2, voffA);
;             PG8_WAIT_V(8); PG8_WAIT_L(0); PG8_BAR; PG8_MMA(1, 0, At, B0); PG8_MMA(1, 1, At, B1); PG8_BAR; PG8_SCHED;
.Lnl_pl_pe:
	s_add_i32 s9, 0, 0x14000
	v_add_u32_e32 v144, s15, v221
	v_add_u32_e32 v160, s9, v221
	ds_read_b128 v[132:135], v144
	ds_read_b128 v[136:139], v144 offset:1024
	ds_read_b128 v[140:143], v144 offset:2048
	ds_read_b128 v[144:147], v144 offset:3072
	ds_read_b128 v[148:151], v160
	ds_read_b128 v[152:155], v160 offset:1024
	ds_read_b128 v[156:159], v160 offset:2048
	ds_read_b128 v[160:163], v160 offset:3072
	s_add_i32 m0, s27, 0xc000
	ds_read_b128 v[178:181], v223
	ds_read_b128 v[182:185], v223 offset:1024
	ds_read_b128 v[186:189], v223 offset:2048
	ds_read_b128 v[190:193], v223 offset:3072
	ds_read_b128 v[198:201], v223 offset:4096
	ds_read_b128 v[202:205], v223 offset:5120
	ds_read_b128 v[206:209], v223 offset:6144
	ds_read_b128 v[210:213], v223 offset:7168
	global_load_lds_dwordx4 v174, s[0:1]
	s_add_i32 m0, s27, 0xe000
	s_nop 0
	global_load_lds_dwordx4 v176, s[0:1]
	s_waitcnt vmcnt(8)
	s_waitcnt lgkmcnt(0)
	s_barrier
	s_setprio 1
	v_mfma_f32_16x16x32_bf16 v[128:131], v[132:135], v[178:181], 0
	v_mfma_f32_16x16x32_bf16 v[124:127], v[140:143], v[178:181], 0
	v_mfma_f32_16x16x32_bf16 v[112:115], v[132:135], v[186:189], 0
	v_mfma_f32_16x16x32_bf16 v[108:111], v[140:143], v[186:189], 0
	v_mfma_f32_16x16x32_bf16 v[96:99], v[132:135], v[198:201], 0
	v_mfma_f32_16x16x32_bf16 v[92:95], v[140:143], v[198:201], 0
	v_mfma_f32_16x16x32_bf16 v[80:83], v[132:135], v[206:209], 0
	v_mfma_f32_16x16x32_bf16 v[76:79], v[140:143], v[206:209], 0
	v_mfma_f32_16x16x32_bf16 v[128:131], v[136:139], v[182:185], v[128:131]
	v_mfma_f32_16x16x32_bf16 v[124:127], v[144:147], v[182:185], v[124:127]
	v_mfma_f32_16x16x32_bf16 v[112:115], v[136:139], v[190:193], v[112:115]
	v_mfma_f32_16x16x32_bf16 v[108:111], v[144:147], v[190:193], v[108:111]
	v_mfma_f32_16x16x32_bf16 v[96:99], v[136:139], v[202:205], v[96:99]
	v_mfma_f32_16x16x32_bf16 v[92:95], v[144:147], v[202:205], v[92:95]
	v_mfma_f32_16x16x32_bf16 v[80:83], v[136:139], v[210:213], v[80:83]
	v_mfma_f32_16x16x32_bf16 v[76:79], v[144:147], v[210:213], v[76:79]
	s_setprio 0
	s_setprio 1
	v_mfma_f32_16x16x32_bf16 v[120:123], v[148:151], v[178:181], 0
	v_mfma_f32_16x16x32_bf16 v[116:119], v[156:159], v[178:181], 0
	v_mfma_f32_16x16x32_bf16 v[104:107], v[148:151], v[186:189], 0
	v_mfma_f32_16x16x32_bf16 v[100:103], v[156:159], v[186:189], 0
	v_mfma_f32_16x16x32_bf16 v[88:91], v[148:151], v[198:201], 0
	v_mfma_f32_16x16x32_bf16 v[84:87], v[156:159], v[198:201], 0
	v_mfma_f32_16x16x32_bf16 v[72:75], v[148:151], v[206:209], 0
	v_mfma_f32_16x16x32_bf16 v[68:71], v[156:159], v[206:209], 0
	v_mfma_f32_16x16x32_bf16 v[120:123], v[152:155], v[182:185], v[120:123]
	v_mfma_f32_16x16x32_bf16 v[116:119], v[160:163], v[182:185], v[116:119]
	v_mfma_f32_16x16x32_bf16 v[104:107], v[152:155], v[190:193], v[104:107]
	v_mfma_f32_16x16x32_bf16 v[100:103], v[160:163], v[190:193], v[100:103]
	v_mfma_f32_16x16x32_bf16 v[88:91], v[152:155], v[202:205], v[88:91]
	v_mfma_f32_16x16x32_bf16 v[84:87], v[160:163], v[202:205], v[84:87]
	v_mfma_f32_16x16x32_bf16 v[72:75], v[152:155], v[210:213], v[72:75]
	v_mfma_f32_16x16x32_bf16 v[68:71], v[160:163], v[210:213], v[68:71]
	s_setprio 0
	s_barrier
	s_add_i32 s15, s15, s26
	s_mov_b32 m0, s15
	ds_read_b128 v[178:181], v223 offset:16384
	ds_read_b128 v[182:185], v223 offset:17408
	ds_read_b128 v[186:189], v223 offset:18432
	ds_read_b128 v[190:193], v223 offset:19456
	ds_read_b128 v[198:201], v223 offset:20480
	ds_read_b128 v[202:205], v223 offset:21504
	ds_read_b128 v[206:209], v223 offset:22528
	ds_read_b128 v[210:213], v223 offset:23552
	global_load_lds_dwordx4 v2, s[16:17]
	s_add_i32 m0, s15, 0x2000
	s_add_i32 s9, s9, s26
	global_load_lds_dwordx4 v168, s[16:17]
	s_add_u32 s16, s16, s18
	s_addc_u32 s17, s17, s19
	s_mov_b64 vcc, s[16:17]
	s_sub_u32 s98, s16, s18
	s_subb_u32 s99, s17, s19
	s_mov_b32 m0, s9
	s_nop 0
	global_load_lds_dwordx4 v2, s[16:17]
	s_add_i32 m0, s9, 0x2000
	s_nop 0
	global_load_lds_dwordx4 v168, s[16:17]
	s_mov_b32 m0, s27
	s_nop 0
	global_load_lds_dwordx4 v164, s[4:5]
	s_mov_b32 m0, s36
	s_nop 0
	global_load_lds_dwordx4 v166, s[4:5]
	s_waitcnt vmcnt(8)
	s_waitcnt lgkmcnt(0)
	s_barrier
	s_setprio 1
	v_mfma_f32_16x16x32_bf16 v[64:67], v[132:135], v[178:181], 0
	v_mfma_f32_16x16x32_bf16 v[60:63], v[140:143], v[178:181], 0
	v_mfma_f32_16x16x32_bf16 v[48:51], v[132:135], v[186:189], 0
	v_mfma_f32_16x16x32_bf16 v[44:47], v[140:143], v[186:189], 0
	v_mfma_f32_16x16x32_bf16 v[32:35], v[132:135], v[198:201], 0
	v_mfma_f32_16x16x32_bf16 v[28:31], v[140:143], v[198:201], 0
	v_mfma_f32_16x16x32_bf16 v[16:19], v[132:135], v[206:209], 0
	v_mfma_f32_16x16x32_bf16 v[12:15], v[140:143], v[206:209], 0
	v_mfma_f32_16x16x32_bf16 v[64:67], v[136:139], v[182:185], v[64:67]
	v_mfma_f32_16x16x32_bf16 v[60:63], v[144:147], v[182:185], v[60:63]
	v_mfma_f32_16x16x32_bf16 v[48:51], v[136:139], v[190:193], v[48:51]
	v_mfma_f32_16x16x32_bf16 v[44:47], v[144:147], v[190:193], v[44:47]
	v_mfma_f32_16x16x32_bf16 v[32:35], v[136:139], v[202:205], v[32:35]
	v_mfma_f32_16x16x32_bf16 v[28:31], v[144:147], v[202:205], v[28:31]
	v_mfma_f32_16x16x32_bf16 v[16:19], v[136:139], v[210:213], v[16:19]
	v_mfma_f32_16x16x32_bf16 v[12:15], v[144:147], v[210:213], v[12:15]
	s_setprio 0
	s_setprio 1
	v_mfma_f32_16x16x32_bf16 v[56:59], v[148:151], v[178:181], 0
	v_mfma_f32_16x16x32_bf16 v[52:55], v[156:159], v[178:181], 0
	v_mfma_f32_16x16x32_bf16 v[40:43], v[148:151], v[186:189], 0
	v_mfma_f32_16x16x32_bf16 v[36:39], v[156:159], v[186:189], 0
	v_mfma_f32_16x16x32_bf16 v[24:27], v[148:151], v[198:201], 0
	v_mfma_f32_16x16x32_bf16 v[20:23], v[156:159], v[198:201], 0
	v_mfma_f32_16x16x32_bf16 v[8:11], v[148:151], v[206:209], 0
	v_mfma_f32_16x16x32_bf16 v[4:7], v[156:159], v[206:209], 0
	v_mfma_f32_16x16x32_bf16 v[56:59], v[152:155], v[182:185], v[56:59]
	v_mfma_f32_16x16x32_bf16 v[52:55], v[160:163], v[182:185], v[52:55]
	v_mfma_f32_16x16x32_bf16 v[40:43], v[152:155], v[190:193], v[40:43]
	v_mfma_f32_16x16x32_bf16 v[36:39], v[160:163], v[190:193], v[36:39]
	v_mfma_f32_16x16x32_bf16 v[24:27], v[152:155], v[202:205], v[24:27]
	v_mfma_f32_16x16x32_bf16 v[20:23], v[160:163], v[202:205], v[20:23]
	v_mfma_f32_16x16x32_bf16 v[8:11], v[152:155], v[210:213], v[8:11]
	v_mfma_f32_16x16x32_bf16 v[4:7], v[160:163], v[210:213], v[4:7]
	s_setprio 0
	s_barrier
	s_branch .Lpe_join_431
	.p2align	8
